# v77 + light residual-epilogue touch: only the first epilogue batch's xres lines and the ga lines are touched during the last K iteration
# baseline (speedup 1.0000x reference)
; #define PG8_STAGE(bufoff, gbase, voff) do { _Pragma("unroll") for (int _i = 0; _i < 2; ++_i) \
;         __builtin_amdgcn_global_load_lds((const unsigned*)((const char*)(gbase) + (voff)[_i]), (PG8_LAS unsigned*)(lds + (bufoff) + ldsw + _i * 8192), 16, 0, 0); } while (0)
; #define PG8_LDA(dst, b, h) do { _Pragma("unroll") for (int m = 0; m < 4; ++m) _Pragma("unroll") for (int k = 0; k < 2; ++k) dst[m][k] = *(const PG8_LAS bf16x8*)(lds + PG8_SA(b, h) + aoff + m * 2048 + k * 1024); } while (0)
; #define PG8_LDB(dst, b, h) do { _Pragma("unroll") for (int n = 0; n < 2; ++n) _Pragma("unroll") for (int k = 0; k < 2; ++k) dst[n][k] = *(const PG8_LAS bf16x8*)(lds + PG8_SB(b, h) + boff + n * 2048 + k * 1024); } while (0)
; #define PG8_MMA(ai, bj, At, Bt) do { __builtin_amdgcn_s_setprio(1); _Pragma("unroll") for (int m = 0; m < 4; ++m) _Pragma("unroll") for (int n = 0; n < 2; ++n) _Pragma("unroll") for (int k = 0; k < 2; ++k) \
;         acc[ai][bj][m][n] = __builtin_amdgcn_mfma_f32_16x16x32_bf16(Bt[n][k], At[m][k], acc[ai][bj][m][n], 0, 0, 0); __builtin_amdgcn_s_setprio(0); } while (0)
; #define PG8_WAIT_V(n) asm volatile("s_waitcnt vmcnt(" #n ")" ::: "memory")
; #define PG8_WAIT_L(n) asm volatile("s_waitcnt lgkmcnt(" #n ")" ::: "memory")
; #define PG8_BAR __builtin_amdgcn_s_barrier()
; template <class Epi, class Sched, bool ALIGN_EPI = false, bool SP2 = false, bool ATILED = false, bool BTILED = false>
; __device__ __forceinline__ void gemm_phase(PG8_LAS unsigned char* lds, const Gemm g, const Sched& S, const Epi& E, const int tid) {
;     ...
;             const bool last = (t == nt - 2);
;             const char* a1 = cA + (size_t)(t + 1) * kstepA;
;             const char* a2 = last ? nA : cA + (size_t)(t + 2) * kstepA; const char* b2 = last ? nB : cB + (size_t)(t + 2) * kstepB;
;             const char* a3 = a2 + kstepA; const char* b3 = b2 + kstepB;
;             if (last && has_next) S.a_ready(nxt);
;             if constexpr (SP2) {
;             PG8_LDB(B0, 0, 0); PG8_LDB(B1, 0, 1); PG8_SCHED; PG8_LDA(At, 0, 0); PG8_STAGE(PG8_SA(1, 1), a1 + hstepA, voffA);
;             PG8_WAIT_V(8); PG8_WAIT_L(0); PG8_BAR; PG8_MMA(0, 0, At, B0); PG8_MMA(0, 1, At, B1); PG8_BAR; PG8_SCHED;
;             PG8_LDA(At, 0, 1); PG8_STAGE(PG8_SB(0, 0), b2, voffB); PG8_STAGE(PG8_SB(0, 1), b2 + hstepB, voffB); PG8_STAGE(PG8_SA(0, 0), a2, voffA);
.LBB0_233:
	s_add_u32 s52, s28, 0x4000
	s_addc_u32 s53, s29, 0
	s_cmp_eq_u32 s72, 12
	s_cselect_b32 s56, s18, s52
	s_cselect_b32 s57, s11, s53
	s_cselect_b32 s54, s19, s25
	s_cselect_b32 s55, s9, s27
	s_add_u32 s52, s56, 0x8000
	s_addc_u32 s53, s57, 0
	s_add_i32 s73, 0, 0x10000
	s_add_i32 s76, 0, 0x14000
	v_add_u32_e32 v142, s73, v177
	v_add_u32_e32 v170, s76, v177
	ds_read_b128 v[130:133], v142
	ds_read_b128 v[134:137], v142 offset:1024
	ds_read_b128 v[138:141], v142 offset:2048
	ds_read_b128 v[142:145], v142 offset:3072
	ds_read_b128 v[146:149], v170
	ds_read_b128 v[162:165], v170 offset:1024
	ds_read_b128 v[166:169], v170 offset:2048
	ds_read_b128 v[170:173], v170 offset:3072
	v_lshl_add_u64 v[174:175], s[28:29], 0, v[158:159]
	s_add_i32 m0, s62, 0xc000
	ds_read_b128 v[180:183], v186
	ds_read_b128 v[188:191], v186 offset:1024
	ds_read_b128 v[196:199], v186 offset:2048
	ds_read_b128 v[200:203], v186 offset:3072
	ds_read_b128 v[204:207], v186 offset:4096
	ds_read_b128 v[208:211], v186 offset:5120
	ds_read_b128 v[212:215], v186 offset:6144
	ds_read_b128 v[216:219], v186 offset:7168
	global_load_lds_dwordx4 v[174:175], off
	v_lshl_add_u64 v[174:175], s[28:29], 0, v[160:161]
	s_add_i32 m0, s62, 0xe000
	s_nop 0
	global_load_lds_dwordx4 v[174:175], off
	s_waitcnt vmcnt(8)
	s_waitcnt lgkmcnt(0)
	s_barrier
	s_setprio 1
	s_waitcnt lgkmcnt(0)
	v_mfma_f32_16x16x32_bf16 v[126:129], v[130:133], v[180:183], v[126:129]
	v_mfma_f32_16x16x32_bf16 v[122:125], v[138:141], v[180:183], v[122:125]
	v_mfma_f32_16x16x32_bf16 v[118:121], v[130:133], v[196:199], v[118:121]
	v_mfma_f32_16x16x32_bf16 v[114:117], v[138:141], v[196:199], v[114:117]
	v_mfma_f32_16x16x32_bf16 v[110:113], v[130:133], v[204:207], v[110:113]
	v_mfma_f32_16x16x32_bf16 v[106:109], v[138:141], v[204:207], v[106:109]
	v_mfma_f32_16x16x32_bf16 v[102:105], v[130:133], v[212:215], v[102:105]
	v_mfma_f32_16x16x32_bf16 v[98:101], v[138:141], v[212:215], v[98:101]
	v_mfma_f32_16x16x32_bf16 v[126:129], v[134:137], v[188:191], v[126:129]
	v_mfma_f32_16x16x32_bf16 v[122:125], v[142:145], v[188:191], v[122:125]
	v_mfma_f32_16x16x32_bf16 v[118:121], v[134:137], v[200:203], v[118:121]
	v_mfma_f32_16x16x32_bf16 v[114:117], v[142:145], v[200:203], v[114:117]
	v_mfma_f32_16x16x32_bf16 v[110:113], v[134:137], v[208:211], v[110:113]
	v_mfma_f32_16x16x32_bf16 v[106:109], v[142:145], v[208:211], v[106:109]
	v_mfma_f32_16x16x32_bf16 v[102:105], v[134:137], v[216:219], v[102:105]
	v_mfma_f32_16x16x32_bf16 v[98:101], v[142:145], v[216:219], v[98:101]
	s_setprio 0
	s_setprio 1
	v_mfma_f32_16x16x32_bf16 v[94:97], v[146:149], v[180:183], v[94:97]
	v_mfma_f32_16x16x32_bf16 v[90:93], v[166:169], v[180:183], v[90:93]
	v_mfma_f32_16x16x32_bf16 v[86:89], v[146:149], v[196:199], v[86:89]
	v_mfma_f32_16x16x32_bf16 v[82:85], v[166:169], v[196:199], v[82:85]
	v_mfma_f32_16x16x32_bf16 v[78:81], v[146:149], v[204:207], v[78:81]
	v_mfma_f32_16x16x32_bf16 v[74:77], v[166:169], v[204:207], v[74:77]
	v_mfma_f32_16x16x32_bf16 v[70:73], v[146:149], v[212:215], v[70:73]
	v_mfma_f32_16x16x32_bf16 v[66:69], v[166:169], v[212:215], v[66:69]
	v_mfma_f32_16x16x32_bf16 v[94:97], v[162:165], v[188:191], v[94:97]
	v_mfma_f32_16x16x32_bf16 v[90:93], v[170:173], v[188:191], v[90:93]
	v_mfma_f32_16x16x32_bf16 v[86:89], v[162:165], v[200:203], v[86:89]
	v_mfma_f32_16x16x32_bf16 v[82:85], v[170:173], v[200:203], v[82:85]
	v_mfma_f32_16x16x32_bf16 v[78:81], v[162:165], v[208:211], v[78:81]
	v_mfma_f32_16x16x32_bf16 v[74:77], v[170:173], v[208:211], v[74:77]
	v_mfma_f32_16x16x32_bf16 v[70:73], v[162:165], v[216:219], v[70:73]
	v_mfma_f32_16x16x32_bf16 v[66:69], v[170:173], v[216:219], v[66:69]
	s_setprio 0
	s_barrier
	s_add_i32 s73, s73, s61
	v_lshl_add_u64 v[174:175], s[54:55], 0, v[152:153]
	s_mov_b32 m0, s73
	ds_read_b128 v[180:183], v186 offset:16384
	ds_read_b128 v[188:191], v186 offset:17408
	ds_read_b128 v[196:199], v186 offset:18432
	ds_read_b128 v[200:203], v186 offset:19456
	ds_read_b128 v[204:207], v186 offset:20480
	ds_read_b128 v[208:211], v186 offset:21504
	ds_read_b128 v[212:215], v186 offset:22528
	ds_read_b128 v[216:219], v186 offset:23552
	global_load_lds_dwordx4 v[174:175], off
	s_add_i32 m0, s73, 0x2000
	s_add_u32 s74, s54, 0x4000
	v_lshl_add_u64 v[174:175], s[54:55], 0, v[156:157]
	s_addc_u32 s75, s55, 0
	s_add_i32 s73, s76, s61
	global_load_lds_dwordx4 v[174:175], off
	v_lshl_add_u64 v[174:175], s[74:75], 0, v[152:153]
	s_mov_b32 m0, s73
	s_nop 0
	global_load_lds_dwordx4 v[174:175], off
	v_lshl_add_u64 v[174:175], s[74:75], 0, v[156:157]
	s_add_i32 m0, s73, 0x2000
	s_nop 0
	global_load_lds_dwordx4 v[174:175], off
	v_lshl_add_u64 v[174:175], s[56:57], 0, v[150:151]
	s_mov_b32 m0, s62
	s_nop 0
	global_load_lds_dwordx4 v[174:175], off
	v_lshl_add_u64 v[174:175], s[56:57], 0, v[154:155]
	s_mov_b32 m0, s63
	s_nop 0
	global_load_lds_dwordx4 v[174:175], off
	s_waitcnt vmcnt(8)
	s_waitcnt lgkmcnt(0)
	s_barrier
; #define PG8_STAGE(bufoff, gbase, voff) do { _Pragma("unroll") for (int _i = 0; _i < 2; ++_i) \
;         __builtin_amdgcn_global_load_lds((const unsigned*)((const char*)(gbase) + (voff)[_i]), (PG8_LAS unsigned*)(lds + (bufoff) + ldsw + _i * 8192), 16, 0, 0); } while (0)
; #define PG8_LDA(dst, b, h) do { _Pragma("unroll") for (int m = 0; m < 4; ++m) _Pragma("unroll") for (int k = 0; k < 2; ++k) dst[m][k] = *(const PG8_LAS bf16x8*)(lds + PG8_SA(b, h) + aoff + m * 2048 + k * 1024); } while (0)
; #define PG8_LDB(dst, b, h) do { _Pragma("unroll") for (int n = 0; n < 2; ++n) _Pragma("unroll") for (int k = 0; k < 2; ++k) dst[n][k] = *(const PG8_LAS bf16x8*)(lds + PG8_SB(b, h) + boff + n * 2048 + k * 1024); } while (0)
; #define PG8_MMA(ai, bj, At, Bt) do { __builtin_amdgcn_s_setprio(1); _Pragma("unroll") for (int m = 0; m < 4; ++m) _Pragma("unroll") for (int n = 0; n < 2; ++n) _Pragma("unroll") for (int k = 0; k < 2; ++k) \
;         acc[ai][bj][m][n] = __builtin_amdgcn_mfma_f32_16x16x32_bf16(Bt[n][k], At[m][k], acc[ai][bj][m][n], 0, 0, 0); __builtin_amdgcn_s_setprio(0); } while (0)
; #define PG8_WAIT_V(n) asm volatile("s_waitcnt vmcnt(" #n ")" ::: "memory")
; #define PG8_WAIT_L(n) asm volatile("s_waitcnt lgkmcnt(" #n ")" ::: "memory")
; #define PG8_BAR __builtin_amdgcn_s_barrier()
; #define PG8_SCHED __builtin_amdgcn_sched_barrier(0)
; template <class Epi, class Sched, bool ALIGN_EPI = false, bool SP2 = false, bool ATILED = false, bool BTILED = false>
; __device__ __forceinline__ void gemm_phase(PG8_LAS unsigned char* lds, const Gemm g, const Sched& S, const Epi& E, const int tid) {
;     ...
;             PG8_WAIT_V(8); PG8_WAIT_L(0); PG8_BAR; PG8_MMA(1, 0, At, B0); PG8_MMA(1, 1, At, B1); PG8_BAR; PG8_SCHED;
;             PG8_LDB(B0, 1, 0); PG8_LDB(B1, 1, 1); PG8_SCHED; PG8_LDA(At, 1, 0); PG8_STAGE(PG8_SA(0, 1), a2 + hstepA, voffA);
;             PG8_WAIT_V(8); PG8_WAIT_L(0); PG8_BAR; PG8_MMA(0, 0, At, B0); PG8_MMA(0, 1, At, B1); PG8_BAR; PG8_SCHED;
	s_setprio 1
	s_waitcnt lgkmcnt(0)
	v_mfma_f32_16x16x32_bf16 v[62:65], v[130:133], v[180:183], v[62:65]
	v_mfma_f32_16x16x32_bf16 v[58:61], v[138:141], v[180:183], v[58:61]
	v_mfma_f32_16x16x32_bf16 v[54:57], v[130:133], v[196:199], v[54:57]
	v_mfma_f32_16x16x32_bf16 v[50:53], v[138:141], v[196:199], v[50:53]
	v_mfma_f32_16x16x32_bf16 v[46:49], v[130:133], v[204:207], v[46:49]
	v_mfma_f32_16x16x32_bf16 v[42:45], v[138:141], v[204:207], v[42:45]
	v_mfma_f32_16x16x32_bf16 v[38:41], v[130:133], v[212:215], v[38:41]
	v_mfma_f32_16x16x32_bf16 v[34:37], v[138:141], v[212:215], v[34:37]
	v_mfma_f32_16x16x32_bf16 v[62:65], v[134:137], v[188:191], v[62:65]
	v_mfma_f32_16x16x32_bf16 v[58:61], v[142:145], v[188:191], v[58:61]
	v_mfma_f32_16x16x32_bf16 v[54:57], v[134:137], v[200:203], v[54:57]
	v_mfma_f32_16x16x32_bf16 v[50:53], v[142:145], v[200:203], v[50:53]
	v_mfma_f32_16x16x32_bf16 v[46:49], v[134:137], v[208:211], v[46:49]
	v_mfma_f32_16x16x32_bf16 v[42:45], v[142:145], v[208:211], v[42:45]
	v_mfma_f32_16x16x32_bf16 v[38:41], v[134:137], v[216:219], v[38:41]
	v_mfma_f32_16x16x32_bf16 v[34:37], v[142:145], v[216:219], v[34:37]
	s_setprio 0
	s_setprio 1
	v_mfma_f32_16x16x32_bf16 v[30:33], v[146:149], v[180:183], v[30:33]
	v_mfma_f32_16x16x32_bf16 v[26:29], v[166:169], v[180:183], v[26:29]
	v_mfma_f32_16x16x32_bf16 v[22:25], v[146:149], v[196:199], v[22:25]
	v_mfma_f32_16x16x32_bf16 v[18:21], v[166:169], v[196:199], v[18:21]
	v_mfma_f32_16x16x32_bf16 v[14:17], v[146:149], v[204:207], v[14:17]
	v_mfma_f32_16x16x32_bf16 v[10:13], v[166:169], v[204:207], v[10:13]
	v_mfma_f32_16x16x32_bf16 v[6:9], v[146:149], v[212:215], v[6:9]
	v_mfma_f32_16x16x32_bf16 v[2:5], v[166:169], v[212:215], v[2:5]
	v_mfma_f32_16x16x32_bf16 v[30:33], v[162:165], v[188:191], v[30:33]
	v_mfma_f32_16x16x32_bf16 v[26:29], v[170:173], v[188:191], v[26:29]
	v_mfma_f32_16x16x32_bf16 v[22:25], v[162:165], v[200:203], v[22:25]
	v_mfma_f32_16x16x32_bf16 v[18:21], v[170:173], v[200:203], v[18:21]
	v_mfma_f32_16x16x32_bf16 v[14:17], v[162:165], v[208:211], v[14:17]
	v_mfma_f32_16x16x32_bf16 v[10:13], v[170:173], v[208:211], v[10:13]
	v_mfma_f32_16x16x32_bf16 v[6:9], v[162:165], v[216:219], v[6:9]
	v_mfma_f32_16x16x32_bf16 v[2:5], v[170:173], v[216:219], v[2:5]
	s_setprio 0
	s_barrier
	s_add_i32 s73, 0, 0x18000
	s_add_i32 s74, 0, 0x1c000
	v_add_u32_e32 v142, s73, v177
	v_add_u32_e32 v170, s74, v177
	ds_read_b128 v[130:133], v142
	ds_read_b128 v[134:137], v142 offset:1024
	ds_read_b128 v[138:141], v142 offset:2048
	ds_read_b128 v[142:145], v142 offset:3072
	ds_read_b128 v[146:149], v170
	ds_read_b128 v[162:165], v170 offset:1024
	ds_read_b128 v[166:169], v170 offset:2048
	ds_read_b128 v[170:173], v170 offset:3072
	s_add_u32 s56, s56, 0x4000
	s_addc_u32 s57, s57, 0
	s_mov_b32 m0, s64
	v_lshl_add_u64 v[174:175], s[56:57], 0, v[150:151]
	ds_read_b128 v[180:183], v186 offset:32768
	ds_read_b128 v[188:191], v186 offset:33792
	ds_read_b128 v[196:199], v186 offset:34816
	ds_read_b128 v[200:203], v186 offset:35840
	ds_read_b128 v[204:207], v186 offset:36864
	ds_read_b128 v[208:211], v186 offset:37888
	ds_read_b128 v[212:215], v186 offset:38912
	ds_read_b128 v[216:219], v186 offset:39936
	global_load_lds_dwordx4 v[174:175], off
	v_lshl_add_u64 v[174:175], s[56:57], 0, v[154:155]
	s_mov_b32 m0, s65
	s_nop 0
	global_load_lds_dwordx4 v[174:175], off
	s_waitcnt vmcnt(8)
	s_waitcnt lgkmcnt(0)
	s_barrier
; #define PG8_STAGE(bufoff, gbase, voff) do { _Pragma("unroll") for (int _i = 0; _i < 2; ++_i) \
;         __builtin_amdgcn_global_load_lds((const unsigned*)((const char*)(gbase) + (voff)[_i]), (PG8_LAS unsigned*)(lds + (bufoff) + ldsw + _i * 8192), 16, 0, 0); } while (0)
; #define PG8_LDA(dst, b, h) do { _Pragma("unroll") for (int m = 0; m < 4; ++m) _Pragma("unroll") for (int k = 0; k < 2; ++k) dst[m][k] = *(const PG8_LAS bf16x8*)(lds + PG8_SA(b, h) + aoff + m * 2048 + k * 1024); } while (0)
; #define PG8_MMA(ai, bj, At, Bt) do { __builtin_amdgcn_s_setprio(1); _Pragma("unroll") for (int m = 0; m < 4; ++m) _Pragma("unroll") for (int n = 0; n < 2; ++n) _Pragma("unroll") for (int k = 0; k < 2; ++k) \
;         acc[ai][bj][m][n] = __builtin_amdgcn_mfma_f32_16x16x32_bf16(Bt[n][k], At[m][k], acc[ai][bj][m][n], 0, 0, 0); __builtin_amdgcn_s_setprio(0); } while (0)
; #define PG8_WAIT_V(n) asm volatile("s_waitcnt vmcnt(" #n ")" ::: "memory")
; #define PG8_WAIT_L(n) asm volatile("s_waitcnt lgkmcnt(" #n ")" ::: "memory")
; #define PG8_BAR __builtin_amdgcn_s_barrier()
; #define PG8_SCHED __builtin_amdgcn_sched_barrier(0)
; #define GAS __attribute__((address_space(1)))
; __device__ __forceinline__ size_t TX(int row, int col) { return ((((size_t)(row >> 8) * 16 + (col >> 6)) * 256 + (row & 255)) << 6) + (col & 63); }
; template <class Epi, class Sched, bool ALIGN_EPI = false, bool SP2 = false, bool ATILED = false, bool BTILED = false>
; __device__ __forceinline__ void gemm_phase(PG8_LAS unsigned char* lds, const Gemm g, const Sched& S, const Epi& E, const int tid) {
;     ...
;             PG8_WAIT_V(8); PG8_WAIT_L(0); PG8_BAR; PG8_MMA(0, 0, At, B0); PG8_MMA(0, 1, At, B1); PG8_BAR; PG8_SCHED;
;             PG8_LDA(At, 1, 1); PG8_STAGE(PG8_SB(1, 0), b3, voffB); PG8_STAGE(PG8_SB(1, 1), b3 + hstepB, voffB); PG8_STAGE(PG8_SA(1, 0), a3, voffA);
;             PG8_WAIT_V(8); PG8_WAIT_L(0); PG8_BAR; PG8_MMA(1, 0, At, B0); PG8_MMA(1, 1, At, B1); PG8_BAR; PG8_SCHED;
;     __device__ __forceinline__ void operator()(const f32x4 (&acc)[2][2][4][2], const pg8::Unit& u, int wr, int wc, int fr, int fq) const {
;     ...
;                 for (int m = 0; m < 4; ++m) xr[m] = *(const GAS u32x4*)(xres + TX(row0 + 128 * ai + 16 * m, col));
; #pragma unroll
;                 for (int n = 0; n < 2; ++n) ga4[n] = *(const GAS f32x4*)(ga + col + 4 * n);
	s_setprio 1
	s_waitcnt lgkmcnt(0)
	v_mfma_f32_16x16x32_bf16 v[126:129], v[130:133], v[180:183], v[126:129]
	v_mfma_f32_16x16x32_bf16 v[122:125], v[138:141], v[180:183], v[122:125]
	v_mfma_f32_16x16x32_bf16 v[118:121], v[130:133], v[196:199], v[118:121]
	v_mfma_f32_16x16x32_bf16 v[114:117], v[138:141], v[196:199], v[114:117]
	v_mfma_f32_16x16x32_bf16 v[110:113], v[130:133], v[204:207], v[110:113]
	v_mfma_f32_16x16x32_bf16 v[106:109], v[138:141], v[204:207], v[106:109]
	v_mfma_f32_16x16x32_bf16 v[102:105], v[130:133], v[212:215], v[102:105]
	v_mfma_f32_16x16x32_bf16 v[98:101], v[138:141], v[212:215], v[98:101]
	v_mfma_f32_16x16x32_bf16 v[126:129], v[134:137], v[188:191], v[126:129]
	v_mfma_f32_16x16x32_bf16 v[122:125], v[142:145], v[188:191], v[122:125]
	v_mfma_f32_16x16x32_bf16 v[118:121], v[134:137], v[200:203], v[118:121]
	v_mfma_f32_16x16x32_bf16 v[114:117], v[142:145], v[200:203], v[114:117]
	v_mfma_f32_16x16x32_bf16 v[110:113], v[134:137], v[208:211], v[110:113]
	v_mfma_f32_16x16x32_bf16 v[106:109], v[142:145], v[208:211], v[106:109]
	v_mfma_f32_16x16x32_bf16 v[102:105], v[134:137], v[216:219], v[102:105]
	v_mfma_f32_16x16x32_bf16 v[98:101], v[142:145], v[216:219], v[98:101]
	s_setprio 0
	s_setprio 1
	v_mfma_f32_16x16x32_bf16 v[94:97], v[146:149], v[180:183], v[94:97]
	v_mfma_f32_16x16x32_bf16 v[90:93], v[166:169], v[180:183], v[90:93]
	v_mfma_f32_16x16x32_bf16 v[86:89], v[146:149], v[196:199], v[86:89]
	v_mfma_f32_16x16x32_bf16 v[82:85], v[166:169], v[196:199], v[82:85]
	v_mfma_f32_16x16x32_bf16 v[78:81], v[146:149], v[204:207], v[78:81]
	v_mfma_f32_16x16x32_bf16 v[74:77], v[166:169], v[204:207], v[74:77]
	v_mfma_f32_16x16x32_bf16 v[70:73], v[146:149], v[212:215], v[70:73]
	v_mfma_f32_16x16x32_bf16 v[66:69], v[166:169], v[212:215], v[66:69]
	v_mfma_f32_16x16x32_bf16 v[94:97], v[162:165], v[188:191], v[94:97]
	v_mfma_f32_16x16x32_bf16 v[90:93], v[170:173], v[188:191], v[90:93]
	v_mfma_f32_16x16x32_bf16 v[86:89], v[162:165], v[200:203], v[86:89]
	v_mfma_f32_16x16x32_bf16 v[82:85], v[170:173], v[200:203], v[82:85]
	v_mfma_f32_16x16x32_bf16 v[78:81], v[162:165], v[208:211], v[78:81]
	v_mfma_f32_16x16x32_bf16 v[74:77], v[170:173], v[208:211], v[74:77]
	v_mfma_f32_16x16x32_bf16 v[70:73], v[162:165], v[216:219], v[70:73]
	v_mfma_f32_16x16x32_bf16 v[66:69], v[170:173], v[216:219], v[66:69]
	s_setprio 0
	s_barrier
	s_add_u32 s56, s54, 0x8000
	s_addc_u32 s57, s55, 0
	s_add_i32 s73, s73, s61
	v_lshl_add_u64 v[174:175], s[56:57], 0, v[152:153]
	s_mov_b32 m0, s73
	ds_read_b128 v[180:183], v186 offset:49152
	ds_read_b128 v[188:191], v186 offset:50176
	ds_read_b128 v[196:199], v186 offset:51200
	ds_read_b128 v[200:203], v186 offset:52224
	ds_read_b128 v[204:207], v186 offset:53248
	ds_read_b128 v[208:211], v186 offset:54272
	ds_read_b128 v[212:215], v186 offset:55296
	ds_read_b128 v[216:219], v186 offset:56320
	global_load_lds_dwordx4 v[174:175], off
	s_add_i32 m0, s73, 0x2000
	s_add_u32 s54, s54, 0xc000
	v_lshl_add_u64 v[174:175], s[56:57], 0, v[156:157]
	s_addc_u32 s55, s55, 0
	s_add_i32 s56, s74, s61
	global_load_lds_dwordx4 v[174:175], off
	v_lshl_add_u64 v[174:175], s[54:55], 0, v[152:153]
	s_mov_b32 m0, s56
	s_nop 0
	global_load_lds_dwordx4 v[174:175], off
	v_lshl_add_u64 v[174:175], s[54:55], 0, v[156:157]
	s_add_i32 m0, s56, 0x2000
	s_nop 0
	global_load_lds_dwordx4 v[174:175], off
	v_lshl_add_u64 v[174:175], s[52:53], 0, v[150:151]
	s_mov_b32 m0, s67
	s_nop 0
	global_load_lds_dwordx4 v[174:175], off
	v_lshl_add_u64 v[174:175], s[52:53], 0, v[154:155]
	s_mov_b32 m0, s68
	s_nop 0
	global_load_lds_dwordx4 v[174:175], off
	s_waitcnt vmcnt(8)
	s_cmp_lg_u32 s72, 12
	s_cbranch_scc1 .Lop_touch_skip
	s_lshl_b32 s98, s24, 4
	s_lshl_b32 s99, s26, 2
	s_add_i32 s98, s98, s99
	s_lshr_b32 s99, s66, 6
	s_add_i32 s98, s98, s99
	s_lshl_b32 s98, s98, 15
	s_lshl_b32 s99, s30, 7
	s_add_i32 s98, s98, s99
	s_and_b32 s99, s66, 63
	s_lshl_b32 s99, s99, 1
	s_add_i32 s98, s98, s99
	v_lshlrev_b32_e32 v253, 7, v1
	v_lshl_add_u32 v253, v176, 1, v253
	v_add_u32_e32 v253, s98, v253
	global_load_dword v231, v253, s[20:21]
	global_load_dword v231, v253, s[20:21] offset:2048
	v_add_u32_e32 v253, 0x1000, v253
	global_load_dword v231, v253, s[20:21]
	global_load_dword v231, v253, s[20:21] offset:2048
	s_lshl_b32 s98, s26, 10
	s_lshl_b32 s99, s66, 2
	s_add_i32 s98, s98, s99
	v_lshl_add_u32 v253, v176, 2, s98
	global_load_dword v231, v253, s[4:5]
	global_load_dword v231, v253, s[4:5] offset:512

; #define PG8_STAGE(bufoff, gbase, voff) do { _Pragma("unroll") for (int _i = 0; _i < 2; ++_i) \
;         __builtin_amdgcn_global_load_lds((const unsigned*)((const char*)(gbase) + (voff)[_i]), (PG8_LAS unsigned*)(lds + (bufoff) + ldsw + _i * 8192), 16, 0, 0); } while (0)
; #define PG8_LDA(dst, b, h) do { _Pragma("unroll") for (int m = 0; m < 4; ++m) _Pragma("unroll") for (int k = 0; k < 2; ++k) dst[m][k] = *(const PG8_LAS bf16x8*)(lds + PG8_SA(b, h) + aoff + m * 2048 + k * 1024); } while (0)
; #define PG8_LDB(dst, b, h) do { _Pragma("unroll") for (int n = 0; n < 2; ++n) _Pragma("unroll") for (int k = 0; k < 2; ++k) dst[n][k] = *(const PG8_LAS bf16x8*)(lds + PG8_SB(b, h) + boff + n * 2048 + k * 1024); } while (0)
; #define PG8_MMA(ai, bj, At, Bt) do { __builtin_amdgcn_s_setprio(1); _Pragma("unroll") for (int m = 0; m < 4; ++m) _Pragma("unroll") for (int n = 0; n < 2; ++n) _Pragma("unroll") for (int k = 0; k < 2; ++k) \
;         acc[ai][bj][m][n] = __builtin_amdgcn_mfma_f32_16x16x32_bf16(Bt[n][k], At[m][k], acc[ai][bj][m][n], 0, 0, 0); __builtin_amdgcn_s_setprio(0); } while (0)
; #define PG8_WAIT_V(n) asm volatile("s_waitcnt vmcnt(" #n ")" ::: "memory")
; #define PG8_WAIT_L(n) asm volatile("s_waitcnt lgkmcnt(" #n ")" ::: "memory")
; #define PG8_BAR __builtin_amdgcn_s_barrier()
; template <class Epi, class Sched, bool ALIGN_EPI = false, bool SP2 = false, bool ATILED = false, bool BTILED = false>
; __device__ __forceinline__ void gemm_phase(PG8_LAS unsigned char* lds, const Gemm g, const Sched& S, const Epi& E, const int tid) {
;     ...
;             const bool last = (t == nt - 2);
;             const char* a1 = cA + (size_t)(t + 1) * kstepA;
;             const char* a2 = last ? nA : cA + (size_t)(t + 2) * kstepA; const char* b2 = last ? nB : cB + (size_t)(t + 2) * kstepB;
;             const char* a3 = a2 + kstepA; const char* b3 = b2 + kstepB;
;             if (last && has_next) S.a_ready(nxt);
;             if constexpr (SP2) {
;             PG8_LDB(B0, 0, 0); PG8_LDB(B1, 0, 1); PG8_SCHED; PG8_LDA(At, 0, 0); PG8_STAGE(PG8_SA(1, 1), a1 + hstepA, voffA);
;             PG8_WAIT_V(8); PG8_WAIT_L(0); PG8_BAR; PG8_MMA(0, 0, At, B0); PG8_MMA(0, 1, At, B1); PG8_BAR; PG8_SCHED;
;             PG8_LDA(At, 0, 1); PG8_STAGE(PG8_SB(0, 0), b2, voffB); PG8_STAGE(PG8_SB(0, 1), b2 + hstepB, voffB); PG8_STAGE(PG8_SA(0, 0), a2, voffA);
.LBB0_478:
	s_add_u32 s18, s16, 0x4000
	s_addc_u32 s19, s17, 0
	s_cmp_eq_u32 s69, 40
	s_cselect_b32 s26, s4, s18
	s_cselect_b32 s27, s5, s19
	s_cselect_b32 s24, s14, s67
	s_cselect_b32 s25, s15, s68
	s_add_u32 s18, s26, 0x8000
	s_addc_u32 s19, s27, 0
	s_add_i32 s70, 0, 0x10000
	s_add_i32 s72, 0, 0x14000
	v_add_u32_e32 v142, s70, v177
	v_add_u32_e32 v170, s72, v177
	ds_read_b128 v[130:133], v142
	ds_read_b128 v[134:137], v142 offset:1024
	ds_read_b128 v[138:141], v142 offset:2048
	ds_read_b128 v[142:145], v142 offset:3072
	ds_read_b128 v[146:149], v170
	ds_read_b128 v[162:165], v170 offset:1024
	ds_read_b128 v[166:169], v170 offset:2048
	ds_read_b128 v[170:173], v170 offset:3072
	v_lshl_add_u64 v[174:175], s[16:17], 0, v[158:159]
	s_add_i32 m0, s53, 0xc000
	ds_read_b128 v[180:183], v184
	ds_read_b128 v[186:189], v184 offset:1024
	ds_read_b128 v[190:193], v184 offset:2048
	ds_read_b128 v[196:199], v184 offset:3072
	ds_read_b128 v[200:203], v184 offset:4096
	ds_read_b128 v[204:207], v184 offset:5120
	ds_read_b128 v[208:211], v184 offset:6144
	ds_read_b128 v[212:215], v184 offset:7168
	global_load_lds_dwordx4 v[174:175], off
	v_lshl_add_u64 v[174:175], s[16:17], 0, v[160:161]
	s_add_i32 m0, s53, 0xe000
	s_nop 0
	global_load_lds_dwordx4 v[174:175], off
	s_waitcnt vmcnt(8)
	s_waitcnt lgkmcnt(0)
	s_barrier
	s_setprio 1
	s_waitcnt lgkmcnt(0)
	v_mfma_f32_16x16x32_bf16 v[126:129], v[130:133], v[180:183], v[126:129]
	v_mfma_f32_16x16x32_bf16 v[122:125], v[138:141], v[180:183], v[122:125]
	v_mfma_f32_16x16x32_bf16 v[118:121], v[130:133], v[190:193], v[118:121]
	v_mfma_f32_16x16x32_bf16 v[114:117], v[138:141], v[190:193], v[114:117]
	v_mfma_f32_16x16x32_bf16 v[110:113], v[130:133], v[200:203], v[110:113]
	v_mfma_f32_16x16x32_bf16 v[106:109], v[138:141], v[200:203], v[106:109]
	v_mfma_f32_16x16x32_bf16 v[102:105], v[130:133], v[208:211], v[102:105]
	v_mfma_f32_16x16x32_bf16 v[98:101], v[138:141], v[208:211], v[98:101]
	v_mfma_f32_16x16x32_bf16 v[126:129], v[134:137], v[186:189], v[126:129]
	v_mfma_f32_16x16x32_bf16 v[122:125], v[142:145], v[186:189], v[122:125]
	v_mfma_f32_16x16x32_bf16 v[118:121], v[134:137], v[196:199], v[118:121]
	v_mfma_f32_16x16x32_bf16 v[114:117], v[142:145], v[196:199], v[114:117]
	v_mfma_f32_16x16x32_bf16 v[110:113], v[134:137], v[204:207], v[110:113]
	v_mfma_f32_16x16x32_bf16 v[106:109], v[142:145], v[204:207], v[106:109]
	v_mfma_f32_16x16x32_bf16 v[102:105], v[134:137], v[212:215], v[102:105]
	v_mfma_f32_16x16x32_bf16 v[98:101], v[142:145], v[212:215], v[98:101]
	s_setprio 0
	s_setprio 1
	v_mfma_f32_16x16x32_bf16 v[94:97], v[146:149], v[180:183], v[94:97]
	v_mfma_f32_16x16x32_bf16 v[90:93], v[166:169], v[180:183], v[90:93]
	v_mfma_f32_16x16x32_bf16 v[86:89], v[146:149], v[190:193], v[86:89]
	v_mfma_f32_16x16x32_bf16 v[82:85], v[166:169], v[190:193], v[82:85]
	v_mfma_f32_16x16x32_bf16 v[78:81], v[146:149], v[200:203], v[78:81]
	v_mfma_f32_16x16x32_bf16 v[74:77], v[166:169], v[200:203], v[74:77]
	v_mfma_f32_16x16x32_bf16 v[70:73], v[146:149], v[208:211], v[70:73]
	v_mfma_f32_16x16x32_bf16 v[66:69], v[166:169], v[208:211], v[66:69]
	v_mfma_f32_16x16x32_bf16 v[94:97], v[162:165], v[186:189], v[94:97]
	v_mfma_f32_16x16x32_bf16 v[90:93], v[170:173], v[186:189], v[90:93]
	v_mfma_f32_16x16x32_bf16 v[86:89], v[162:165], v[196:199], v[86:89]
	v_mfma_f32_16x16x32_bf16 v[82:85], v[170:173], v[196:199], v[82:85]
	v_mfma_f32_16x16x32_bf16 v[78:81], v[162:165], v[204:207], v[78:81]
	v_mfma_f32_16x16x32_bf16 v[74:77], v[170:173], v[204:207], v[74:77]
	v_mfma_f32_16x16x32_bf16 v[70:73], v[162:165], v[212:215], v[70:73]
	v_mfma_f32_16x16x32_bf16 v[66:69], v[170:173], v[212:215], v[66:69]
	s_setprio 0
	s_barrier
	s_add_i32 s70, s70, s52
	v_lshl_add_u64 v[174:175], s[24:25], 0, v[152:153]
	s_mov_b32 m0, s70
	ds_read_b128 v[180:183], v184 offset:16384
	ds_read_b128 v[186:189], v184 offset:17408
	ds_read_b128 v[190:193], v184 offset:18432
	ds_read_b128 v[196:199], v184 offset:19456
	ds_read_b128 v[200:203], v184 offset:20480
	ds_read_b128 v[204:207], v184 offset:21504
	ds_read_b128 v[208:211], v184 offset:22528
	ds_read_b128 v[212:215], v184 offset:23552
	global_load_lds_dwordx4 v[174:175], off
	s_add_i32 m0, s70, 0x2000
	s_add_u32 s70, s24, 0x4000
	v_lshl_add_u64 v[174:175], s[24:25], 0, v[156:157]
	s_addc_u32 s71, s25, 0
	s_add_i32 s72, s72, s52
	global_load_lds_dwordx4 v[174:175], off
	v_lshl_add_u64 v[174:175], s[70:71], 0, v[152:153]
	s_mov_b32 m0, s72
	s_nop 0
	global_load_lds_dwordx4 v[174:175], off
	v_lshl_add_u64 v[174:175], s[70:71], 0, v[156:157]
	s_add_i32 m0, s72, 0x2000
	s_nop 0
	global_load_lds_dwordx4 v[174:175], off
	v_lshl_add_u64 v[174:175], s[26:27], 0, v[150:151]
	s_mov_b32 m0, s53
	s_nop 0
	global_load_lds_dwordx4 v[174:175], off
	v_lshl_add_u64 v[174:175], s[26:27], 0, v[154:155]
	s_mov_b32 m0, s54
	s_nop 0
	global_load_lds_dwordx4 v[174:175], off
	s_waitcnt vmcnt(8)
	s_waitcnt lgkmcnt(0)
	s_barrier
; #define PG8_STAGE(bufoff, gbase, voff) do { _Pragma("unroll") for (int _i = 0; _i < 2; ++_i) \
;         __builtin_amdgcn_global_load_lds((const unsigned*)((const char*)(gbase) + (voff)[_i]), (PG8_LAS unsigned*)(lds + (bufoff) + ldsw + _i * 8192), 16, 0, 0); } while (0)
; #define PG8_LDA(dst, b, h) do { _Pragma("unroll") for (int m = 0; m < 4; ++m) _Pragma("unroll") for (int k = 0; k < 2; ++k) dst[m][k] = *(const PG8_LAS bf16x8*)(lds + PG8_SA(b, h) + aoff + m * 2048 + k * 1024); } while (0)
; #define PG8_LDB(dst, b, h) do { _Pragma("unroll") for (int n = 0; n < 2; ++n) _Pragma("unroll") for (int k = 0; k < 2; ++k) dst[n][k] = *(const PG8_LAS bf16x8*)(lds + PG8_SB(b, h) + boff + n * 2048 + k * 1024); } while (0)
; #define PG8_MMA(ai, bj, At, Bt) do { __builtin_amdgcn_s_setprio(1); _Pragma("unroll") for (int m = 0; m < 4; ++m) _Pragma("unroll") for (int n = 0; n < 2; ++n) _Pragma("unroll") for (int k = 0; k < 2; ++k) \
;         acc[ai][bj][m][n] = __builtin_amdgcn_mfma_f32_16x16x32_bf16(Bt[n][k], At[m][k], acc[ai][bj][m][n], 0, 0, 0); __builtin_amdgcn_s_setprio(0); } while (0)
; #define PG8_WAIT_V(n) asm volatile("s_waitcnt vmcnt(" #n ")" ::: "memory")
; #define PG8_WAIT_L(n) asm volatile("s_waitcnt lgkmcnt(" #n ")" ::: "memory")
; #define PG8_BAR __builtin_amdgcn_s_barrier()
; #define PG8_SCHED __builtin_amdgcn_sched_barrier(0)
; template <class Epi, class Sched, bool ALIGN_EPI = false, bool SP2 = false, bool ATILED = false, bool BTILED = false>
; __device__ __forceinline__ void gemm_phase(PG8_LAS unsigned char* lds, const Gemm g, const Sched& S, const Epi& E, const int tid) {
;     ...
;             PG8_WAIT_V(8); PG8_WAIT_L(0); PG8_BAR; PG8_MMA(1, 0, At, B0); PG8_MMA(1, 1, At, B1); PG8_BAR; PG8_SCHED;
;             PG8_LDB(B0, 1, 0); PG8_LDB(B1, 1, 1); PG8_SCHED; PG8_LDA(At, 1, 0); PG8_STAGE(PG8_SA(0, 1), a2 + hstepA, voffA);
;             PG8_WAIT_V(8); PG8_WAIT_L(0); PG8_BAR; PG8_MMA(0, 0, At, B0); PG8_MMA(0, 1, At, B1); PG8_BAR; PG8_SCHED;
	s_setprio 1
	s_waitcnt lgkmcnt(0)
	v_mfma_f32_16x16x32_bf16 v[62:65], v[130:133], v[180:183], v[62:65]
	v_mfma_f32_16x16x32_bf16 v[58:61], v[138:141], v[180:183], v[58:61]
	v_mfma_f32_16x16x32_bf16 v[54:57], v[130:133], v[190:193], v[54:57]
	v_mfma_f32_16x16x32_bf16 v[50:53], v[138:141], v[190:193], v[50:53]
	v_mfma_f32_16x16x32_bf16 v[46:49], v[130:133], v[200:203], v[46:49]
	v_mfma_f32_16x16x32_bf16 v[42:45], v[138:141], v[200:203], v[42:45]
	v_mfma_f32_16x16x32_bf16 v[38:41], v[130:133], v[208:211], v[38:41]
	v_mfma_f32_16x16x32_bf16 v[34:37], v[138:141], v[208:211], v[34:37]
	v_mfma_f32_16x16x32_bf16 v[62:65], v[134:137], v[186:189], v[62:65]
	v_mfma_f32_16x16x32_bf16 v[58:61], v[142:145], v[186:189], v[58:61]
	v_mfma_f32_16x16x32_bf16 v[54:57], v[134:137], v[196:199], v[54:57]
	v_mfma_f32_16x16x32_bf16 v[50:53], v[142:145], v[196:199], v[50:53]
	v_mfma_f32_16x16x32_bf16 v[46:49], v[134:137], v[204:207], v[46:49]
	v_mfma_f32_16x16x32_bf16 v[42:45], v[142:145], v[204:207], v[42:45]
	v_mfma_f32_16x16x32_bf16 v[38:41], v[134:137], v[212:215], v[38:41]
	v_mfma_f32_16x16x32_bf16 v[34:37], v[142:145], v[212:215], v[34:37]
	s_setprio 0
	s_setprio 1
	v_mfma_f32_16x16x32_bf16 v[30:33], v[146:149], v[180:183], v[30:33]
	v_mfma_f32_16x16x32_bf16 v[26:29], v[166:169], v[180:183], v[26:29]
	v_mfma_f32_16x16x32_bf16 v[22:25], v[146:149], v[190:193], v[22:25]
	v_mfma_f32_16x16x32_bf16 v[18:21], v[166:169], v[190:193], v[18:21]
	v_mfma_f32_16x16x32_bf16 v[14:17], v[146:149], v[200:203], v[14:17]
	v_mfma_f32_16x16x32_bf16 v[10:13], v[166:169], v[200:203], v[10:13]
	v_mfma_f32_16x16x32_bf16 v[6:9], v[146:149], v[208:211], v[6:9]
	v_mfma_f32_16x16x32_bf16 v[2:5], v[166:169], v[208:211], v[2:5]
	v_mfma_f32_16x16x32_bf16 v[30:33], v[162:165], v[186:189], v[30:33]
	v_mfma_f32_16x16x32_bf16 v[26:29], v[170:173], v[186:189], v[26:29]
	v_mfma_f32_16x16x32_bf16 v[22:25], v[162:165], v[196:199], v[22:25]
	v_mfma_f32_16x16x32_bf16 v[18:21], v[170:173], v[196:199], v[18:21]
	v_mfma_f32_16x16x32_bf16 v[14:17], v[162:165], v[204:207], v[14:17]
	v_mfma_f32_16x16x32_bf16 v[10:13], v[170:173], v[204:207], v[10:13]
	v_mfma_f32_16x16x32_bf16 v[6:9], v[162:165], v[212:215], v[6:9]
	v_mfma_f32_16x16x32_bf16 v[2:5], v[170:173], v[212:215], v[2:5]
	s_setprio 0
	s_barrier
	s_add_i32 s70, 0, 0x18000
	s_add_i32 s71, 0, 0x1c000
	v_add_u32_e32 v142, s70, v177
	v_add_u32_e32 v170, s71, v177
	ds_read_b128 v[130:133], v142
	ds_read_b128 v[134:137], v142 offset:1024
	ds_read_b128 v[138:141], v142 offset:2048
	ds_read_b128 v[142:145], v142 offset:3072
	ds_read_b128 v[146:149], v170
	ds_read_b128 v[162:165], v170 offset:1024
	ds_read_b128 v[166:169], v170 offset:2048
	ds_read_b128 v[170:173], v170 offset:3072
	s_add_u32 s26, s26, 0x4000
	s_addc_u32 s27, s27, 0
	s_mov_b32 m0, s55
	v_lshl_add_u64 v[174:175], s[26:27], 0, v[150:151]
	ds_read_b128 v[180:183], v184 offset:32768
	ds_read_b128 v[186:189], v184 offset:33792
	ds_read_b128 v[190:193], v184 offset:34816
	ds_read_b128 v[196:199], v184 offset:35840
	ds_read_b128 v[200:203], v184 offset:36864
	ds_read_b128 v[204:207], v184 offset:37888
	ds_read_b128 v[208:211], v184 offset:38912
	ds_read_b128 v[212:215], v184 offset:39936
	global_load_lds_dwordx4 v[174:175], off
	v_lshl_add_u64 v[174:175], s[26:27], 0, v[154:155]
	s_mov_b32 m0, s56
	s_nop 0
	global_load_lds_dwordx4 v[174:175], off
	s_waitcnt vmcnt(8)
	s_waitcnt lgkmcnt(0)
	s_barrier
; #define PG8_STAGE(bufoff, gbase, voff) do { _Pragma("unroll") for (int _i = 0; _i < 2; ++_i) \
;         __builtin_amdgcn_global_load_lds((const unsigned*)((const char*)(gbase) + (voff)[_i]), (PG8_LAS unsigned*)(lds + (bufoff) + ldsw + _i * 8192), 16, 0, 0); } while (0)
; #define PG8_LDA(dst, b, h) do { _Pragma("unroll") for (int m = 0; m < 4; ++m) _Pragma("unroll") for (int k = 0; k < 2; ++k) dst[m][k] = *(const PG8_LAS bf16x8*)(lds + PG8_SA(b, h) + aoff + m * 2048 + k * 1024); } while (0)
; #define PG8_MMA(ai, bj, At, Bt) do { __builtin_amdgcn_s_setprio(1); _Pragma("unroll") for (int m = 0; m < 4; ++m) _Pragma("unroll") for (int n = 0; n < 2; ++n) _Pragma("unroll") for (int k = 0; k < 2; ++k) \
;         acc[ai][bj][m][n] = __builtin_amdgcn_mfma_f32_16x16x32_bf16(Bt[n][k], At[m][k], acc[ai][bj][m][n], 0, 0, 0); __builtin_amdgcn_s_setprio(0); } while (0)
; #define PG8_WAIT_V(n) asm volatile("s_waitcnt vmcnt(" #n ")" ::: "memory")
; #define PG8_WAIT_L(n) asm volatile("s_waitcnt lgkmcnt(" #n ")" ::: "memory")
; #define PG8_BAR __builtin_amdgcn_s_barrier()
; #define PG8_SCHED __builtin_amdgcn_sched_barrier(0)
; #define GAS __attribute__((address_space(1)))
; __device__ __forceinline__ size_t TX(int row, int col) { return ((((size_t)(row >> 8) * 16 + (col >> 6)) * 256 + (row & 255)) << 6) + (col & 63); }
; template <class Epi, class Sched, bool ALIGN_EPI = false, bool SP2 = false, bool ATILED = false, bool BTILED = false>
; __device__ __forceinline__ void gemm_phase(PG8_LAS unsigned char* lds, const Gemm g, const Sched& S, const Epi& E, const int tid) {
;     ...
;             PG8_WAIT_V(8); PG8_WAIT_L(0); PG8_BAR; PG8_MMA(0, 0, At, B0); PG8_MMA(0, 1, At, B1); PG8_BAR; PG8_SCHED;
;             PG8_LDA(At, 1, 1); PG8_STAGE(PG8_SB(1, 0), b3, voffB); PG8_STAGE(PG8_SB(1, 1), b3 + hstepB, voffB); PG8_STAGE(PG8_SA(1, 0), a3, voffA);
;             PG8_WAIT_V(8); PG8_WAIT_L(0); PG8_BAR; PG8_MMA(1, 0, At, B0); PG8_MMA(1, 1, At, B1); PG8_BAR; PG8_SCHED;
;     __device__ __forceinline__ void operator()(const f32x4 (&acc)[2][2][4][2], const pg8::Unit& u, int wr, int wc, int fr, int fq) const {
;     ...
;                 for (int m = 0; m < 4; ++m) xr[m] = *(const GAS u32x4*)(xres + TX(row0 + 128 * ai + 16 * m, col));
; #pragma unroll
;                 for (int n = 0; n < 2; ++n) ga4[n] = *(const GAS f32x4*)(ga + col + 4 * n);
	s_setprio 1
	s_waitcnt lgkmcnt(0)
	v_mfma_f32_16x16x32_bf16 v[126:129], v[130:133], v[180:183], v[126:129]
	v_mfma_f32_16x16x32_bf16 v[122:125], v[138:141], v[180:183], v[122:125]
	v_mfma_f32_16x16x32_bf16 v[118:121], v[130:133], v[190:193], v[118:121]
	v_mfma_f32_16x16x32_bf16 v[114:117], v[138:141], v[190:193], v[114:117]
	v_mfma_f32_16x16x32_bf16 v[110:113], v[130:133], v[200:203], v[110:113]
	v_mfma_f32_16x16x32_bf16 v[106:109], v[138:141], v[200:203], v[106:109]
	v_mfma_f32_16x16x32_bf16 v[102:105], v[130:133], v[208:211], v[102:105]
	v_mfma_f32_16x16x32_bf16 v[98:101], v[138:141], v[208:211], v[98:101]
	v_mfma_f32_16x16x32_bf16 v[126:129], v[134:137], v[186:189], v[126:129]
	v_mfma_f32_16x16x32_bf16 v[122:125], v[142:145], v[186:189], v[122:125]
	v_mfma_f32_16x16x32_bf16 v[118:121], v[134:137], v[196:199], v[118:121]
	v_mfma_f32_16x16x32_bf16 v[114:117], v[142:145], v[196:199], v[114:117]
	v_mfma_f32_16x16x32_bf16 v[110:113], v[134:137], v[204:207], v[110:113]
	v_mfma_f32_16x16x32_bf16 v[106:109], v[142:145], v[204:207], v[106:109]
	v_mfma_f32_16x16x32_bf16 v[102:105], v[134:137], v[212:215], v[102:105]
	v_mfma_f32_16x16x32_bf16 v[98:101], v[142:145], v[212:215], v[98:101]
	s_setprio 0
	s_setprio 1
	v_mfma_f32_16x16x32_bf16 v[94:97], v[146:149], v[180:183], v[94:97]
	v_mfma_f32_16x16x32_bf16 v[90:93], v[166:169], v[180:183], v[90:93]
	v_mfma_f32_16x16x32_bf16 v[86:89], v[146:149], v[190:193], v[86:89]
	v_mfma_f32_16x16x32_bf16 v[82:85], v[166:169], v[190:193], v[82:85]
	v_mfma_f32_16x16x32_bf16 v[78:81], v[146:149], v[200:203], v[78:81]
	v_mfma_f32_16x16x32_bf16 v[74:77], v[166:169], v[200:203], v[74:77]
	v_mfma_f32_16x16x32_bf16 v[70:73], v[146:149], v[208:211], v[70:73]
	v_mfma_f32_16x16x32_bf16 v[66:69], v[166:169], v[208:211], v[66:69]
	v_mfma_f32_16x16x32_bf16 v[94:97], v[162:165], v[186:189], v[94:97]
	v_mfma_f32_16x16x32_bf16 v[90:93], v[170:173], v[186:189], v[90:93]
	v_mfma_f32_16x16x32_bf16 v[86:89], v[162:165], v[196:199], v[86:89]
	v_mfma_f32_16x16x32_bf16 v[82:85], v[170:173], v[196:199], v[82:85]
	v_mfma_f32_16x16x32_bf16 v[78:81], v[162:165], v[204:207], v[78:81]
	v_mfma_f32_16x16x32_bf16 v[74:77], v[170:173], v[204:207], v[74:77]
	v_mfma_f32_16x16x32_bf16 v[70:73], v[162:165], v[212:215], v[70:73]
	v_mfma_f32_16x16x32_bf16 v[66:69], v[170:173], v[212:215], v[66:69]
	s_setprio 0
	s_barrier
	s_add_u32 s26, s24, 0x8000
	s_addc_u32 s27, s25, 0
	s_add_i32 s70, s70, s52
	v_lshl_add_u64 v[174:175], s[26:27], 0, v[152:153]
	s_mov_b32 m0, s70
	ds_read_b128 v[180:183], v184 offset:49152
	ds_read_b128 v[186:189], v184 offset:50176
	ds_read_b128 v[190:193], v184 offset:51200
	ds_read_b128 v[196:199], v184 offset:52224
	ds_read_b128 v[200:203], v184 offset:53248
	ds_read_b128 v[204:207], v184 offset:54272
	ds_read_b128 v[208:211], v184 offset:55296
	ds_read_b128 v[212:215], v184 offset:56320
	global_load_lds_dwordx4 v[174:175], off
	s_add_i32 m0, s70, 0x2000
	s_add_u32 s24, s24, 0xc000
	v_lshl_add_u64 v[174:175], s[26:27], 0, v[156:157]
	s_addc_u32 s25, s25, 0
	s_add_i32 s26, s71, s52
	global_load_lds_dwordx4 v[174:175], off
	v_lshl_add_u64 v[174:175], s[24:25], 0, v[152:153]
	s_mov_b32 m0, s26
	s_nop 0
	global_load_lds_dwordx4 v[174:175], off
	v_lshl_add_u64 v[174:175], s[24:25], 0, v[156:157]
	s_add_i32 m0, s26, 0x2000
	s_nop 0
	global_load_lds_dwordx4 v[174:175], off
	v_lshl_add_u64 v[174:175], s[18:19], 0, v[150:151]
	s_mov_b32 m0, s58
	s_nop 0
	global_load_lds_dwordx4 v[174:175], off
	v_lshl_add_u64 v[174:175], s[18:19], 0, v[154:155]
	s_mov_b32 m0, s59
	s_nop 0
	global_load_lds_dwordx4 v[174:175], off
	s_waitcnt vmcnt(8)
	s_cmp_lg_u32 s69, 40
	s_cbranch_scc1 .Ldn_touch_skip
	s_lshl_b32 s98, s65, 4
	s_lshl_b32 s99, s66, 2
	s_add_i32 s98, s98, s99
	s_lshr_b32 s99, s57, 6
	s_add_i32 s98, s98, s99
	s_lshl_b32 s98, s98, 15
	s_lshl_b32 s99, s30, 7
	s_add_i32 s98, s98, s99
	s_and_b32 s99, s57, 63
	s_lshl_b32 s99, s99, 1
	s_add_i32 s98, s98, s99
	v_lshlrev_b32_e32 v253, 7, v1
	v_lshl_add_u32 v253, v176, 1, v253
	v_add_u32_e32 v253, s98, v253
	global_load_dword v231, v253, s[20:21]
	global_load_dword v231, v253, s[20:21] offset:2048
	v_add_u32_e32 v253, 0x1000, v253
	global_load_dword v231, v253, s[20:21]
	global_load_dword v231, v253, s[20:21] offset:2048
	s_lshl_b32 s98, s66, 10
	s_lshl_b32 s99, s57, 2
	s_add_i32 s98, s98, s99
	v_lshl_add_u32 v253, v176, 2, s98
	global_load_dword v231, v253, s[6:7]
	global_load_dword v231, v253, s[6:7] offset:512
